# lever 1 waitcnt placement: phase-0 w_in conversion no longer waits on the next item's just-issued loads inside cv_finish (8 vmcnt waits removed per finish, vmcnt(0) added on the no-load entries)
# speedup vs baseline: 1.0083x; 1.0083x over previous
.LBB0_122:
	v_add_u32_e32 v70, s27, v159
	s_mov_b64 s[10:11], -1
	s_cmp_lt_i32 s2, 0
	v_ashrrev_i32_e32 v71, 31, v70
	s_cbranch_scc1 .LBB0_126
	v_add_u32_e32 v72, v147, v148
	v_add_u32_e32 v73, 0x420, v72
	ds_write2_b32 v72, v2, v3 offset1:1
	ds_write2_b32 v72, v4, v5 offset0:2 offset1:3
	ds_write2_b32 v73, v6, v7 offset1:1
	v_add_u32_e32 v73, 0x428, v72
	ds_write2_b32 v73, v8, v9 offset1:1
	v_add_u32_e32 v73, 0x840, v72
	ds_write2_b32 v73, v10, v11 offset1:1
	v_add_u32_e32 v73, 0x848, v72
	ds_write2_b32 v73, v12, v13 offset1:1
	v_add_u32_e32 v73, 0xc60, v72
	ds_write2_b32 v73, v18, v19 offset1:1
	v_add_u32_e32 v73, 0xc68, v72
	ds_write2_b32 v73, v20, v21 offset1:1
	v_add_u32_e32 v73, 0x1080, v72
	ds_write2_b32 v73, v34, v35 offset1:1
	v_add_u32_e32 v73, 0x1088, v72
	ds_write2_b32 v73, v36, v37 offset1:1
	v_add_u32_e32 v73, 0x14a0, v72
	ds_write2_b32 v73, v46, v47 offset1:1
	v_add_u32_e32 v73, 0x14a8, v72
	ds_write2_b32 v73, v48, v49 offset1:1
	v_add_u32_e32 v73, 0x18c0, v72
	ds_write2_b32 v73, v58, v59 offset1:1
	v_add_u32_e32 v73, 0x18c8, v72
	ds_write2_b32 v73, v60, v61 offset1:1
	v_add_u32_e32 v73, 0x1ce0, v72
	v_add_u32_e32 v72, 0x1ce8, v72
	ds_write2_b32 v73, v62, v63 offset1:1
	ds_write2_b32 v72, v64, v65 offset1:1
	s_waitcnt lgkmcnt(0)
	ds_read2_b32 v[72:73], v146 offset1:33
	ds_read2_b32 v[74:75], v146 offset0:66 offset1:99
	ds_read2_b32 v[76:77], v146 offset0:132 offset1:165
	ds_read2_b32 v[78:79], v146 offset0:198 offset1:231
	s_ashr_i32 s5, s4, 31
	v_lshl_add_u64 v[80:81], s[4:5], 1, v[68:69]
	s_waitcnt lgkmcnt(3)
	v_cvt_pk_bf16_f32 v72, v72, v73
	s_waitcnt lgkmcnt(2)
	v_cvt_pk_bf16_f32 v73, v74, v75
	s_waitcnt lgkmcnt(1)
	v_cvt_pk_bf16_f32 v74, v76, v77
	v_lshlrev_b64 v[76:77], 12, v[70:71]
	s_waitcnt lgkmcnt(0)
	v_cvt_pk_bf16_f32 v75, v78, v79
	v_lshl_add_u64 v[76:77], v[80:81], 0, v[76:77]
	global_store_dwordx4 v[76:77], v[72:75], off sc0 sc1
	s_nop 1
	ds_read2_b32 v[72:73], v146 offset0:8 offset1:41
	ds_read2_b32 v[74:75], v146 offset0:74 offset1:107
	ds_read2_b32 v[76:77], v146 offset0:140 offset1:173
	ds_read2_b32 v[78:79], v146 offset0:206 offset1:239
	s_waitcnt lgkmcnt(3)
	v_cvt_pk_bf16_f32 v72, v72, v73
	s_waitcnt lgkmcnt(2)
	v_cvt_pk_bf16_f32 v73, v74, v75
	s_waitcnt lgkmcnt(1)
	v_cvt_pk_bf16_f32 v74, v76, v77
	v_add_u32_e32 v76, s27, v133
	v_ashrrev_i32_e32 v77, 31, v76
	v_lshlrev_b64 v[76:77], 12, v[76:77]
	s_waitcnt lgkmcnt(0)
	v_cvt_pk_bf16_f32 v75, v78, v79
	v_lshl_add_u64 v[76:77], v[80:81], 0, v[76:77]
	global_store_dwordx4 v[76:77], v[72:75], off sc0 sc1
	s_nop 1
	ds_read2_b32 v[72:73], v146 offset0:16 offset1:49
	ds_read2_b32 v[74:75], v146 offset0:82 offset1:115
	ds_read2_b32 v[76:77], v146 offset0:148 offset1:181
	ds_read2_b32 v[78:79], v146 offset0:214 offset1:247
	s_waitcnt lgkmcnt(3)
	v_cvt_pk_bf16_f32 v72, v72, v73
	s_waitcnt lgkmcnt(2)
	v_cvt_pk_bf16_f32 v73, v74, v75
	s_waitcnt lgkmcnt(1)
	v_cvt_pk_bf16_f32 v74, v76, v77
	v_add_u32_e32 v76, s27, v144
	v_ashrrev_i32_e32 v77, 31, v76
	v_lshlrev_b64 v[76:77], 12, v[76:77]
	s_waitcnt lgkmcnt(0)
	v_cvt_pk_bf16_f32 v75, v78, v79
	v_lshl_add_u64 v[76:77], v[80:81], 0, v[76:77]
	global_store_dwordx4 v[76:77], v[72:75], off sc0 sc1
	s_nop 1
	ds_read2_b32 v[72:73], v146 offset0:24 offset1:57
	ds_read2_b32 v[74:75], v146 offset0:90 offset1:123
	ds_read2_b32 v[76:77], v146 offset0:156 offset1:189
	ds_read2_b32 v[78:79], v146 offset0:222 offset1:255
	s_waitcnt lgkmcnt(3)
	v_cvt_pk_bf16_f32 v72, v72, v73
	s_waitcnt lgkmcnt(2)
	v_cvt_pk_bf16_f32 v73, v74, v75
	s_waitcnt lgkmcnt(1)
	v_cvt_pk_bf16_f32 v74, v76, v77
	v_add_u32_e32 v76, s27, v145
	v_ashrrev_i32_e32 v77, 31, v76
	v_lshlrev_b64 v[76:77], 12, v[76:77]
	s_waitcnt lgkmcnt(0)
	v_cvt_pk_bf16_f32 v75, v78, v79
	v_lshl_add_u64 v[76:77], v[80:81], 0, v[76:77]
	global_store_dwordx4 v[76:77], v[72:75], off sc0 sc1
	s_nop 1
	s_waitcnt lgkmcnt(0)
	s_cbranch_execz .LBB0_127

.LBB0_150:
	v_add_u32_e32 v70, s30, v159
	s_mov_b64 s[10:11], -1
	s_cmp_lt_i32 s0, 0
	v_ashrrev_i32_e32 v71, 31, v70
	s_cbranch_scc1 .LBB0_152
	v_add_u32_e32 v72, v147, v148
	v_add_u32_e32 v73, 0x420, v72
	ds_write2_b32 v72, v14, v15 offset1:1
	ds_write2_b32 v72, v16, v17 offset0:2 offset1:3
	ds_write2_b32 v73, v22, v23 offset1:1
	v_add_u32_e32 v73, 0x428, v72
	ds_write2_b32 v73, v24, v25 offset1:1
	v_add_u32_e32 v73, 0x840, v72
	ds_write2_b32 v73, v26, v27 offset1:1
	v_add_u32_e32 v73, 0x848, v72
	ds_write2_b32 v73, v28, v29 offset1:1
	v_add_u32_e32 v73, 0xc60, v72
	ds_write2_b32 v73, v30, v31 offset1:1
	v_add_u32_e32 v73, 0xc68, v72
	ds_write2_b32 v73, v32, v33 offset1:1
	v_add_u32_e32 v73, 0x1080, v72
	ds_write2_b32 v73, v38, v39 offset1:1
	v_add_u32_e32 v73, 0x1088, v72
	ds_write2_b32 v73, v40, v41 offset1:1
	v_add_u32_e32 v73, 0x14a0, v72
	ds_write2_b32 v73, v42, v43 offset1:1
	v_add_u32_e32 v73, 0x14a8, v72
	ds_write2_b32 v73, v44, v45 offset1:1
	v_add_u32_e32 v73, 0x18c0, v72
	ds_write2_b32 v73, v50, v51 offset1:1
	v_add_u32_e32 v73, 0x18c8, v72
	ds_write2_b32 v73, v52, v53 offset1:1
	v_add_u32_e32 v73, 0x1ce0, v72
	v_add_u32_e32 v72, 0x1ce8, v72
	ds_write2_b32 v73, v54, v55 offset1:1
	ds_write2_b32 v72, v56, v57 offset1:1
	s_waitcnt lgkmcnt(0)
	ds_read2_b32 v[72:73], v146 offset1:33
	ds_read2_b32 v[74:75], v146 offset0:66 offset1:99
	ds_read2_b32 v[76:77], v146 offset0:132 offset1:165
	ds_read2_b32 v[78:79], v146 offset0:198 offset1:231
	s_ashr_i32 s7, s6, 31
	v_lshl_add_u64 v[80:81], s[6:7], 1, v[68:69]
	s_waitcnt lgkmcnt(3)
	v_cvt_pk_bf16_f32 v72, v72, v73
	s_waitcnt lgkmcnt(2)
	v_cvt_pk_bf16_f32 v73, v74, v75
	s_waitcnt lgkmcnt(1)
	v_cvt_pk_bf16_f32 v74, v76, v77
	v_lshlrev_b64 v[76:77], 12, v[70:71]
	s_waitcnt lgkmcnt(0)
	v_cvt_pk_bf16_f32 v75, v78, v79
	v_lshl_add_u64 v[76:77], v[80:81], 0, v[76:77]
	global_store_dwordx4 v[76:77], v[72:75], off sc0 sc1
	s_nop 1
	ds_read2_b32 v[72:73], v146 offset0:8 offset1:41
	ds_read2_b32 v[74:75], v146 offset0:74 offset1:107
	ds_read2_b32 v[76:77], v146 offset0:140 offset1:173
	ds_read2_b32 v[78:79], v146 offset0:206 offset1:239
	s_mov_b64 s[10:11], 0
	s_waitcnt lgkmcnt(3)
	v_cvt_pk_bf16_f32 v72, v72, v73
	s_waitcnt lgkmcnt(2)
	v_cvt_pk_bf16_f32 v73, v74, v75
	s_waitcnt lgkmcnt(1)
	v_cvt_pk_bf16_f32 v74, v76, v77
	v_add_u32_e32 v76, s30, v133
	v_ashrrev_i32_e32 v77, 31, v76
	v_lshlrev_b64 v[76:77], 12, v[76:77]
	s_waitcnt lgkmcnt(0)
	v_cvt_pk_bf16_f32 v75, v78, v79
	v_lshl_add_u64 v[76:77], v[80:81], 0, v[76:77]
	global_store_dwordx4 v[76:77], v[72:75], off sc0 sc1
	s_nop 1
	ds_read2_b32 v[72:73], v146 offset0:16 offset1:49
	ds_read2_b32 v[74:75], v146 offset0:82 offset1:115
	ds_read2_b32 v[76:77], v146 offset0:148 offset1:181
	ds_read2_b32 v[78:79], v146 offset0:214 offset1:247
	s_waitcnt lgkmcnt(3)
	v_cvt_pk_bf16_f32 v72, v72, v73
	s_waitcnt lgkmcnt(2)
	v_cvt_pk_bf16_f32 v73, v74, v75
	s_waitcnt lgkmcnt(1)
	v_cvt_pk_bf16_f32 v74, v76, v77
	v_add_u32_e32 v76, s30, v144
	v_ashrrev_i32_e32 v77, 31, v76
	v_lshlrev_b64 v[76:77], 12, v[76:77]
	s_waitcnt lgkmcnt(0)
	v_cvt_pk_bf16_f32 v75, v78, v79
	v_lshl_add_u64 v[76:77], v[80:81], 0, v[76:77]
	global_store_dwordx4 v[76:77], v[72:75], off sc0 sc1
	s_nop 1
	ds_read2_b32 v[72:73], v146 offset0:24 offset1:57
	ds_read2_b32 v[74:75], v146 offset0:90 offset1:123
	ds_read2_b32 v[76:77], v146 offset0:156 offset1:189
	ds_read2_b32 v[78:79], v146 offset0:222 offset1:255
	s_waitcnt lgkmcnt(3)
	v_cvt_pk_bf16_f32 v72, v72, v73
	s_waitcnt lgkmcnt(2)
	v_cvt_pk_bf16_f32 v73, v74, v75
	s_waitcnt lgkmcnt(1)
	v_cvt_pk_bf16_f32 v74, v76, v77
	v_add_u32_e32 v76, s30, v145
	v_ashrrev_i32_e32 v77, 31, v76
	v_lshlrev_b64 v[76:77], 12, v[76:77]
	s_waitcnt lgkmcnt(0)
	v_cvt_pk_bf16_f32 v75, v78, v79
	v_lshl_add_u64 v[76:77], v[80:81], 0, v[76:77]
	global_store_dwordx4 v[76:77], v[72:75], off sc0 sc1
	s_nop 1
	s_waitcnt lgkmcnt(0)
